# GEMM epilogues keep the row scales in spare VGPRs across the K-loop and fetch the next unit's ssq partials under the current unit's math/stores (load latency off the epilogue path)
# baseline (speedup 1.0000x reference)
;     __device__ __forceinline__ void operator()(const f32x4 (&acc)[2][2][4][2], const Unit& u, int wr, int wc, int fr, int fq) const {
;     ...
;             for (int m = 0; m < 4; ++m) { const int row = row0 + ai * HALF + m * 16; const f32x4 q0 = *(const f32x4*)(ssq + (size_t)row * 16), q1 = *(const f32x4*)(ssq + (size_t)row * 16 + 4), q2 = *(const f32x4*)(ssq + (size_t)row * 16 + 8), q3 = *(const f32x4*)(ssq + (size_t)row * 16 + 12);
;                 const float rs = rsqrtf(((((q0[0] + q0[1]) + (q0[2] + q0[3])) + ((q1[0] + q1[1]) + (q1[2] + q1[3]))) + (((q2[0] + q2[1]) + (q2[2] + q2[3])) + ((q3[0] + q3[1]) + (q3[2] + q3[3])))) * (1.0f / 1024.0f) + 1e-6f);
.LBB0_610:
	v_readlane_b32 s28, v253, 45
	v_readlane_b32 s29, v253, 46
	v_xor_b32_e32 v228, 16, v214
	v_lshlrev_b32_e32 v228, 2, v228
	v_xor_b32_e32 v229, 32, v214
	v_lshlrev_b32_e32 v229, 2, v229
	s_cmp_eq_u32 s53, 1
	s_cbranch_scc0 .Lsw_have_rs
	v_lshl_add_u32 v192, s55, 8, v147
	v_and_b32_e32 v193, 24, v149
	v_lshlrev_b32_e32 v193, 1, v193
	v_lshl_add_u32 v193, v192, 6, v193
	v_add_u32_e32 v230, 0x2000, v193
	global_load_dwordx4 v[152:155], v193, s[16:17]
	global_load_dwordx4 v[156:159], v193, s[16:17] offset:1024
	global_load_dwordx4 v[160:163], v193, s[16:17] offset:2048
	global_load_dwordx4 v[164:167], v193, s[16:17] offset:3072
	global_load_dwordx4 v[168:171], v230, s[16:17]
	global_load_dwordx4 v[172:175], v230, s[16:17] offset:1024
	global_load_dwordx4 v[176:179], v230, s[16:17] offset:2048
	global_load_dwordx4 v[180:183], v230, s[16:17] offset:3072
	s_waitcnt vmcnt(7)
	v_add_f32_e32 v154, v154, v155
	v_add_f32_e32 v194, v152, v153
	v_add_f32_e32 v194, v194, v154
	s_waitcnt vmcnt(6)
	v_add_f32_e32 v158, v158, v159
	v_add_f32_e32 v195, v156, v157
	v_add_f32_e32 v195, v195, v158
	s_waitcnt vmcnt(5)
	v_add_f32_e32 v162, v162, v163
	v_add_f32_e32 v196, v160, v161
	v_add_f32_e32 v196, v196, v162
	s_waitcnt vmcnt(4)
	v_add_f32_e32 v166, v166, v167
	v_add_f32_e32 v197, v164, v165
	v_add_f32_e32 v197, v197, v166
	s_waitcnt vmcnt(3)
	v_add_f32_e32 v170, v170, v171
	v_add_f32_e32 v204, v168, v169
	v_add_f32_e32 v204, v204, v170
	s_waitcnt vmcnt(2)
	v_add_f32_e32 v174, v174, v175
	v_add_f32_e32 v205, v172, v173
	v_add_f32_e32 v205, v205, v174
	s_waitcnt vmcnt(1)
	v_add_f32_e32 v178, v178, v179
	v_add_f32_e32 v206, v176, v177
	v_add_f32_e32 v206, v206, v178
	s_waitcnt vmcnt(0)
	v_add_f32_e32 v182, v182, v183
	v_add_f32_e32 v207, v180, v181
	v_add_f32_e32 v207, v207, v182
	ds_bpermute_b32 v220, v228, v194
	ds_bpermute_b32 v221, v228, v195
	ds_bpermute_b32 v222, v228, v196
	ds_bpermute_b32 v223, v228, v197
	ds_bpermute_b32 v224, v228, v204
	ds_bpermute_b32 v225, v228, v205
	ds_bpermute_b32 v226, v228, v206
	ds_bpermute_b32 v227, v228, v207
	s_waitcnt lgkmcnt(7)
	v_add_f32_e32 v194, v194, v220
	s_waitcnt lgkmcnt(6)
	v_add_f32_e32 v195, v195, v221
	s_waitcnt lgkmcnt(5)
	v_add_f32_e32 v196, v196, v222
	s_waitcnt lgkmcnt(4)
	v_add_f32_e32 v197, v197, v223
	s_waitcnt lgkmcnt(3)
	v_add_f32_e32 v204, v204, v224
	s_waitcnt lgkmcnt(2)
	v_add_f32_e32 v205, v205, v225
	s_waitcnt lgkmcnt(1)
	v_add_f32_e32 v206, v206, v226
	s_waitcnt lgkmcnt(0)
	v_add_f32_e32 v207, v207, v227
	ds_bpermute_b32 v220, v229, v194
	ds_bpermute_b32 v221, v229, v195
	ds_bpermute_b32 v222, v229, v196
	ds_bpermute_b32 v223, v229, v197
	ds_bpermute_b32 v224, v229, v204
	ds_bpermute_b32 v225, v229, v205
	ds_bpermute_b32 v226, v229, v206
	ds_bpermute_b32 v227, v229, v207
	s_waitcnt lgkmcnt(7)
	v_add_f32_e32 v194, v194, v220
	s_waitcnt lgkmcnt(6)
	v_add_f32_e32 v195, v195, v221
	s_waitcnt lgkmcnt(5)
	v_add_f32_e32 v196, v196, v222
	s_waitcnt lgkmcnt(4)
	v_add_f32_e32 v197, v197, v223
	s_waitcnt lgkmcnt(3)
	v_add_f32_e32 v204, v204, v224
	s_waitcnt lgkmcnt(2)
	v_add_f32_e32 v205, v205, v225
	s_waitcnt lgkmcnt(1)
	v_add_f32_e32 v206, v206, v226
	s_waitcnt lgkmcnt(0)
	v_add_f32_e32 v207, v207, v227
	v_fmamk_f32 v194, v194, 0x3a800000, v208
	v_fmamk_f32 v195, v195, 0x3a800000, v208
	v_fmamk_f32 v196, v196, 0x3a800000, v208
	v_fmamk_f32 v197, v197, 0x3a800000, v208
	v_fmamk_f32 v204, v204, 0x3a800000, v208
	v_fmamk_f32 v205, v205, 0x3a800000, v208
	v_fmamk_f32 v206, v206, 0x3a800000, v208
	v_fmamk_f32 v207, v207, 0x3a800000, v208
	v_rsq_f32_e32 v242, v194
	v_rsq_f32_e32 v243, v195
	v_rsq_f32_e32 v244, v196
	v_rsq_f32_e32 v245, v197
	v_rsq_f32_e32 v246, v204
	v_rsq_f32_e32 v247, v205
	v_rsq_f32_e32 v248, v206
	v_rsq_f32_e32 v249, v207
.Lsw_have_rs:
	s_and_b64 vcc, exec, s[2:3]
	s_cbranch_vccz .Lsw_nonext1
	v_lshl_add_u32 v192, s22, 8, v147
	v_and_b32_e32 v193, 24, v149
	v_lshlrev_b32_e32 v193, 1, v193
	v_lshl_add_u32 v193, v192, 6, v193
	v_add_u32_e32 v230, 0x2000, v193
	global_load_dwordx4 v[152:155], v193, s[16:17]
	global_load_dwordx4 v[156:159], v193, s[16:17] offset:1024
	global_load_dwordx4 v[160:163], v193, s[16:17] offset:2048
	global_load_dwordx4 v[164:167], v193, s[16:17] offset:3072
	global_load_dwordx4 v[168:171], v230, s[16:17]
	global_load_dwordx4 v[172:175], v230, s[16:17] offset:1024
	global_load_dwordx4 v[176:179], v230, s[16:17] offset:2048
	global_load_dwordx4 v[180:183], v230, s[16:17] offset:3072
; __device__ __forceinline__ unsigned cvt_pk_bf16(float lo, float hi) { unsigned r; asm volatile("v_cvt_pk_bf16_f32 %0, %1, %2" : "=v"(r) : "v"(lo), "v"(hi)); return r; }
;     __device__ __forceinline__ void operator()(const f32x4 (&acc)[2][2][4][2], const Unit& u, int wr, int wc, int fr, int fq) const {
;     ...
;             for (int m = 0; m < 4; ++m) { const int row = row0 + ai * HALF + m * 16; const f32x4 q0 = *(const f32x4*)(ssq + (size_t)row * 16), q1 = *(const f32x4*)(ssq + (size_t)row * 16 + 4), q2 = *(const f32x4*)(ssq + (size_t)row * 16 + 8), q3 = *(const f32x4*)(ssq + (size_t)row * 16 + 12);
;                 const float rs = rsqrtf(((((q0[0] + q0[1]) + (q0[2] + q0[3])) + ((q1[0] + q1[1]) + (q1[2] + q1[3]))) + (((q2[0] + q2[1]) + (q2[2] + q2[3])) + ((q3[0] + q3[1]) + (q3[2] + q3[3])))) * (1.0f / 1024.0f) + 1e-6f);
;                 float a[8];
; #pragma unroll
;                 for (int n = 0; n < 2; ++n)
; #pragma unroll
;                     for (int j = 0; j < 4; ++j) { const float g = acc[ai][0][m][n][j] * rs, up = acc[ai][1][m][n][j] * rs; a[4 * n + j] = g * up * __builtin_amdgcn_rcpf(1.0f + __expf(-g)); }
;                 u32x4 w; w.x = cvt_pk_bf16(a[0], a[1]); w.y = cvt_pk_bf16(a[2], a[3]); w.z = cvt_pk_bf16(a[4], a[5]); w.w = cvt_pk_bf16(a[6], a[7]);
;                 *(u32x4*)(O + (size_t)row * ldc + col0) = w; }
.Lsw_nonext1:
	v_lshl_add_u32 v192, s55, 8, v147
	s_movk_i32 s21, 0x1600
	v_lshl_or_b32 v231, s54, 7, v149
	v_lshlrev_b32_e32 v231, 1, v231
	v_mad_u32_u24 v184, v192, s21, v231
	v_add_u32_e32 v185, 0x16000, v184
	v_add_u32_e32 v186, 0x16000, v185
	v_add_u32_e32 v187, 0x16000, v186
	v_add_u32_e32 v188, 0xb0000, v184
	v_add_u32_e32 v189, 0xb0000, v185
	v_add_u32_e32 v190, 0xb0000, v186
	v_add_u32_e32 v191, 0xb0000, v187
	v_mov_b32_e32 v232, v242
	v_pk_mul_f32 v[128:129], v[128:129], v[232:233] op_sel_hi:[1,0]
	v_pk_mul_f32 v[130:131], v[130:131], v[232:233] op_sel_hi:[1,0]
	v_pk_mul_f32 v[120:121], v[120:121], v[232:233] op_sel_hi:[1,0]
	v_pk_mul_f32 v[122:123], v[122:123], v[232:233] op_sel_hi:[1,0]
	v_pk_mul_f32 v[124:125], v[124:125], v[232:233] op_sel_hi:[1,0]
	v_pk_mul_f32 v[126:127], v[126:127], v[232:233] op_sel_hi:[1,0]
	v_pk_mul_f32 v[116:117], v[116:117], v[232:233] op_sel_hi:[1,0]
	v_pk_mul_f32 v[118:119], v[118:119], v[232:233] op_sel_hi:[1,0]
	v_mul_f32_e32 v124, v128, v124
	v_mul_f32_e32 v125, v129, v125
	v_mul_f32_e32 v126, v130, v126
	v_mul_f32_e32 v127, v131, v127
	v_mul_f32_e32 v116, v120, v116
	v_mul_f32_e32 v117, v121, v117
	v_mul_f32_e32 v118, v122, v118
	v_mul_f32_e32 v119, v123, v119
	v_mul_f32_e32 v128, 0xbfb8aa3b, v128
	v_mul_f32_e32 v129, 0xbfb8aa3b, v129
	v_mul_f32_e32 v130, 0xbfb8aa3b, v130
	v_mul_f32_e32 v131, 0xbfb8aa3b, v131
	v_mul_f32_e32 v120, 0xbfb8aa3b, v120
	v_mul_f32_e32 v121, 0xbfb8aa3b, v121
	v_mul_f32_e32 v122, 0xbfb8aa3b, v122
	v_mul_f32_e32 v123, 0xbfb8aa3b, v123
	v_exp_f32_e32 v128, v128
	v_exp_f32_e32 v129, v129
	v_exp_f32_e32 v130, v130
	v_exp_f32_e32 v131, v131
	v_exp_f32_e32 v120, v120
	v_exp_f32_e32 v121, v121
	v_exp_f32_e32 v122, v122
	v_exp_f32_e32 v123, v123
	v_add_f32_e32 v128, 1.0, v128
	v_add_f32_e32 v129, 1.0, v129
	v_add_f32_e32 v130, 1.0, v130
	v_add_f32_e32 v131, 1.0, v131
	v_add_f32_e32 v120, 1.0, v120
	v_add_f32_e32 v121, 1.0, v121
	v_add_f32_e32 v122, 1.0, v122
	v_add_f32_e32 v123, 1.0, v123
	v_rcp_f32_e32 v128, v128
	v_rcp_f32_e32 v129, v129
	v_rcp_f32_e32 v130, v130
	v_rcp_f32_e32 v131, v131
	v_rcp_f32_e32 v120, v120
	v_rcp_f32_e32 v121, v121
	v_rcp_f32_e32 v122, v122
	v_rcp_f32_e32 v123, v123
	v_mul_f32_e32 v128, v124, v128
	v_mul_f32_e32 v129, v125, v129
	v_mul_f32_e32 v130, v126, v130
	v_mul_f32_e32 v131, v127, v131
	v_mul_f32_e32 v120, v116, v120
	v_mul_f32_e32 v121, v117, v121
	v_mul_f32_e32 v122, v118, v122
	v_mul_f32_e32 v123, v119, v123
	v_cvt_pk_bf16_f32 v128, v128, v129
	v_cvt_pk_bf16_f32 v129, v130, v131
	v_cvt_pk_bf16_f32 v130, v120, v121
	v_cvt_pk_bf16_f32 v131, v122, v123
	global_store_dwordx4 v184, v[128:131], s[28:29]
	v_mov_b32_e32 v232, v243
	v_pk_mul_f32 v[112:113], v[112:113], v[232:233] op_sel_hi:[1,0]
	v_pk_mul_f32 v[114:115], v[114:115], v[232:233] op_sel_hi:[1,0]
	v_pk_mul_f32 v[104:105], v[104:105], v[232:233] op_sel_hi:[1,0]
	v_pk_mul_f32 v[106:107], v[106:107], v[232:233] op_sel_hi:[1,0]
	v_pk_mul_f32 v[108:109], v[108:109], v[232:233] op_sel_hi:[1,0]
	v_pk_mul_f32 v[110:111], v[110:111], v[232:233] op_sel_hi:[1,0]
	v_pk_mul_f32 v[100:101], v[100:101], v[232:233] op_sel_hi:[1,0]
	v_pk_mul_f32 v[102:103], v[102:103], v[232:233] op_sel_hi:[1,0]
	v_mul_f32_e32 v108, v112, v108
	v_mul_f32_e32 v109, v113, v109
	v_mul_f32_e32 v110, v114, v110
	v_mul_f32_e32 v111, v115, v111
	v_mul_f32_e32 v100, v104, v100
	v_mul_f32_e32 v101, v105, v101
	v_mul_f32_e32 v102, v106, v102
	v_mul_f32_e32 v103, v107, v103
	v_mul_f32_e32 v112, 0xbfb8aa3b, v112
	v_mul_f32_e32 v113, 0xbfb8aa3b, v113
	v_mul_f32_e32 v114, 0xbfb8aa3b, v114
	v_mul_f32_e32 v115, 0xbfb8aa3b, v115
	v_mul_f32_e32 v104, 0xbfb8aa3b, v104
	v_mul_f32_e32 v105, 0xbfb8aa3b, v105
	v_mul_f32_e32 v106, 0xbfb8aa3b, v106
	v_mul_f32_e32 v107, 0xbfb8aa3b, v107
	v_exp_f32_e32 v112, v112
	v_exp_f32_e32 v113, v113
	v_exp_f32_e32 v114, v114
	v_exp_f32_e32 v115, v115
	v_exp_f32_e32 v104, v104
	v_exp_f32_e32 v105, v105
	v_exp_f32_e32 v106, v106
	v_exp_f32_e32 v107, v107
	v_add_f32_e32 v112, 1.0, v112
	v_add_f32_e32 v113, 1.0, v113
	v_add_f32_e32 v114, 1.0, v114
	v_add_f32_e32 v115, 1.0, v115
	v_add_f32_e32 v104, 1.0, v104
	v_add_f32_e32 v105, 1.0, v105
	v_add_f32_e32 v106, 1.0, v106
	v_add_f32_e32 v107, 1.0, v107
	v_rcp_f32_e32 v112, v112
	v_rcp_f32_e32 v113, v113
	v_rcp_f32_e32 v114, v114
	v_rcp_f32_e32 v115, v115
	v_rcp_f32_e32 v104, v104
	v_rcp_f32_e32 v105, v105
	v_rcp_f32_e32 v106, v106
	v_rcp_f32_e32 v107, v107
	v_mul_f32_e32 v112, v108, v112
	v_mul_f32_e32 v113, v109, v113
	v_mul_f32_e32 v114, v110, v114
	v_mul_f32_e32 v115, v111, v115
	v_mul_f32_e32 v104, v100, v104
	v_mul_f32_e32 v105, v101, v105
	v_mul_f32_e32 v106, v102, v106
	v_mul_f32_e32 v107, v103, v107
	v_cvt_pk_bf16_f32 v112, v112, v113
	v_cvt_pk_bf16_f32 v113, v114, v115
	v_cvt_pk_bf16_f32 v114, v104, v105
	v_cvt_pk_bf16_f32 v115, v106, v107
	global_store_dwordx4 v185, v[112:115], s[28:29]
	v_mov_b32_e32 v232, v244
	v_pk_mul_f32 v[96:97], v[96:97], v[232:233] op_sel_hi:[1,0]
	v_pk_mul_f32 v[98:99], v[98:99], v[232:233] op_sel_hi:[1,0]
	v_pk_mul_f32 v[88:89], v[88:89], v[232:233] op_sel_hi:[1,0]
	v_pk_mul_f32 v[90:91], v[90:91], v[232:233] op_sel_hi:[1,0]
	v_pk_mul_f32 v[92:93], v[92:93], v[232:233] op_sel_hi:[1,0]
	v_pk_mul_f32 v[94:95], v[94:95], v[232:233] op_sel_hi:[1,0]
	v_pk_mul_f32 v[84:85], v[84:85], v[232:233] op_sel_hi:[1,0]
	v_pk_mul_f32 v[86:87], v[86:87], v[232:233] op_sel_hi:[1,0]
	v_mul_f32_e32 v92, v96, v92
	v_mul_f32_e32 v93, v97, v93
	v_mul_f32_e32 v94, v98, v94
	v_mul_f32_e32 v95, v99, v95
	v_mul_f32_e32 v84, v88, v84
	v_mul_f32_e32 v85, v89, v85
	v_mul_f32_e32 v86, v90, v86
	v_mul_f32_e32 v87, v91, v87
	v_mul_f32_e32 v96, 0xbfb8aa3b, v96
; __device__ __forceinline__ unsigned cvt_pk_bf16(float lo, float hi) { unsigned r; asm volatile("v_cvt_pk_bf16_f32 %0, %1, %2" : "=v"(r) : "v"(lo), "v"(hi)); return r; }
;     __device__ __forceinline__ void operator()(const f32x4 (&acc)[2][2][4][2], const Unit& u, int wr, int wc, int fr, int fq) const {
;     ...
;             for (int m = 0; m < 4; ++m) { const int row = row0 + ai * HALF + m * 16; const f32x4 q0 = *(const f32x4*)(ssq + (size_t)row * 16), q1 = *(const f32x4*)(ssq + (size_t)row * 16 + 4), q2 = *(const f32x4*)(ssq + (size_t)row * 16 + 8), q3 = *(const f32x4*)(ssq + (size_t)row * 16 + 12);
;                 const float rs = rsqrtf(((((q0[0] + q0[1]) + (q0[2] + q0[3])) + ((q1[0] + q1[1]) + (q1[2] + q1[3]))) + (((q2[0] + q2[1]) + (q2[2] + q2[3])) + ((q3[0] + q3[1]) + (q3[2] + q3[3])))) * (1.0f / 1024.0f) + 1e-6f);
;                 float a[8];
; #pragma unroll
;                 for (int n = 0; n < 2; ++n)
; #pragma unroll
;                     for (int j = 0; j < 4; ++j) { const float g = acc[ai][0][m][n][j] * rs, up = acc[ai][1][m][n][j] * rs; a[4 * n + j] = g * up * __builtin_amdgcn_rcpf(1.0f + __expf(-g)); }
;                 u32x4 w; w.x = cvt_pk_bf16(a[0], a[1]); w.y = cvt_pk_bf16(a[2], a[3]); w.z = cvt_pk_bf16(a[4], a[5]); w.w = cvt_pk_bf16(a[6], a[7]);
;                 *(u32x4*)(O + (size_t)row * ldc + col0) = w; }
	v_mul_f32_e32 v97, 0xbfb8aa3b, v97
	v_mul_f32_e32 v98, 0xbfb8aa3b, v98
	v_mul_f32_e32 v99, 0xbfb8aa3b, v99
	v_mul_f32_e32 v88, 0xbfb8aa3b, v88
	v_mul_f32_e32 v89, 0xbfb8aa3b, v89
	v_mul_f32_e32 v90, 0xbfb8aa3b, v90
	v_mul_f32_e32 v91, 0xbfb8aa3b, v91
	v_exp_f32_e32 v96, v96
	v_exp_f32_e32 v97, v97
	v_exp_f32_e32 v98, v98
	v_exp_f32_e32 v99, v99
	v_exp_f32_e32 v88, v88
	v_exp_f32_e32 v89, v89
	v_exp_f32_e32 v90, v90
	v_exp_f32_e32 v91, v91
	v_add_f32_e32 v96, 1.0, v96
	v_add_f32_e32 v97, 1.0, v97
	v_add_f32_e32 v98, 1.0, v98
	v_add_f32_e32 v99, 1.0, v99
	v_add_f32_e32 v88, 1.0, v88
	v_add_f32_e32 v89, 1.0, v89
	v_add_f32_e32 v90, 1.0, v90
	v_add_f32_e32 v91, 1.0, v91
	v_rcp_f32_e32 v96, v96
	v_rcp_f32_e32 v97, v97
	v_rcp_f32_e32 v98, v98
	v_rcp_f32_e32 v99, v99
	v_rcp_f32_e32 v88, v88
	v_rcp_f32_e32 v89, v89
	v_rcp_f32_e32 v90, v90
	v_rcp_f32_e32 v91, v91
	v_mul_f32_e32 v96, v92, v96
	v_mul_f32_e32 v97, v93, v97
	v_mul_f32_e32 v98, v94, v98
	v_mul_f32_e32 v99, v95, v99
	v_mul_f32_e32 v88, v84, v88
	v_mul_f32_e32 v89, v85, v89
	v_mul_f32_e32 v90, v86, v90
	v_mul_f32_e32 v91, v87, v91
	v_cvt_pk_bf16_f32 v96, v96, v97
	v_cvt_pk_bf16_f32 v97, v98, v99
	v_cvt_pk_bf16_f32 v98, v88, v89
	v_cvt_pk_bf16_f32 v99, v90, v91
	global_store_dwordx4 v186, v[96:99], s[28:29]
	v_mov_b32_e32 v232, v245
	v_pk_mul_f32 v[80:81], v[80:81], v[232:233] op_sel_hi:[1,0]
	v_pk_mul_f32 v[82:83], v[82:83], v[232:233] op_sel_hi:[1,0]
	v_pk_mul_f32 v[72:73], v[72:73], v[232:233] op_sel_hi:[1,0]
	v_pk_mul_f32 v[74:75], v[74:75], v[232:233] op_sel_hi:[1,0]
	v_pk_mul_f32 v[76:77], v[76:77], v[232:233] op_sel_hi:[1,0]
	v_pk_mul_f32 v[78:79], v[78:79], v[232:233] op_sel_hi:[1,0]
	v_pk_mul_f32 v[68:69], v[68:69], v[232:233] op_sel_hi:[1,0]
	v_pk_mul_f32 v[70:71], v[70:71], v[232:233] op_sel_hi:[1,0]
	v_mul_f32_e32 v76, v80, v76
	v_mul_f32_e32 v77, v81, v77
	v_mul_f32_e32 v78, v82, v78
	v_mul_f32_e32 v79, v83, v79
	v_mul_f32_e32 v68, v72, v68
	v_mul_f32_e32 v69, v73, v69
	v_mul_f32_e32 v70, v74, v70
	v_mul_f32_e32 v71, v75, v71
	v_mul_f32_e32 v80, 0xbfb8aa3b, v80
	v_mul_f32_e32 v81, 0xbfb8aa3b, v81
	v_mul_f32_e32 v82, 0xbfb8aa3b, v82
	v_mul_f32_e32 v83, 0xbfb8aa3b, v83
	v_mul_f32_e32 v72, 0xbfb8aa3b, v72
	v_mul_f32_e32 v73, 0xbfb8aa3b, v73
	v_mul_f32_e32 v74, 0xbfb8aa3b, v74
	v_mul_f32_e32 v75, 0xbfb8aa3b, v75
	v_exp_f32_e32 v80, v80
	v_exp_f32_e32 v81, v81
	v_exp_f32_e32 v82, v82
	v_exp_f32_e32 v83, v83
	v_exp_f32_e32 v72, v72
	v_exp_f32_e32 v73, v73
	v_exp_f32_e32 v74, v74
	v_exp_f32_e32 v75, v75
	v_add_f32_e32 v80, 1.0, v80
	v_add_f32_e32 v81, 1.0, v81
	v_add_f32_e32 v82, 1.0, v82
	v_add_f32_e32 v83, 1.0, v83
	v_add_f32_e32 v72, 1.0, v72
	v_add_f32_e32 v73, 1.0, v73
	v_add_f32_e32 v74, 1.0, v74
	v_add_f32_e32 v75, 1.0, v75
	v_rcp_f32_e32 v80, v80
	v_rcp_f32_e32 v81, v81
	v_rcp_f32_e32 v82, v82
	v_rcp_f32_e32 v83, v83
	v_rcp_f32_e32 v72, v72
	v_rcp_f32_e32 v73, v73
	v_rcp_f32_e32 v74, v74
	v_rcp_f32_e32 v75, v75
	v_mul_f32_e32 v80, v76, v80
	v_mul_f32_e32 v81, v77, v81
	v_mul_f32_e32 v82, v78, v82
	v_mul_f32_e32 v83, v79, v83
	v_mul_f32_e32 v72, v68, v72
	v_mul_f32_e32 v73, v69, v73
	v_mul_f32_e32 v74, v70, v74
	v_mul_f32_e32 v75, v71, v75
	v_cvt_pk_bf16_f32 v80, v80, v81
	v_cvt_pk_bf16_f32 v81, v82, v83
	v_cvt_pk_bf16_f32 v82, v72, v73
	v_cvt_pk_bf16_f32 v83, v74, v75
	global_store_dwordx4 v187, v[80:83], s[28:29]
	v_mov_b32_e32 v232, v246
	v_pk_mul_f32 v[64:65], v[64:65], v[232:233] op_sel_hi:[1,0]
	v_pk_mul_f32 v[66:67], v[66:67], v[232:233] op_sel_hi:[1,0]
	v_pk_mul_f32 v[56:57], v[56:57], v[232:233] op_sel_hi:[1,0]
	v_pk_mul_f32 v[58:59], v[58:59], v[232:233] op_sel_hi:[1,0]
	v_pk_mul_f32 v[60:61], v[60:61], v[232:233] op_sel_hi:[1,0]
	v_pk_mul_f32 v[62:63], v[62:63], v[232:233] op_sel_hi:[1,0]
	v_pk_mul_f32 v[52:53], v[52:53], v[232:233] op_sel_hi:[1,0]
	v_pk_mul_f32 v[54:55], v[54:55], v[232:233] op_sel_hi:[1,0]
	v_mul_f32_e32 v60, v64, v60
	v_mul_f32_e32 v61, v65, v61
	v_mul_f32_e32 v62, v66, v62
	v_mul_f32_e32 v63, v67, v63
	v_mul_f32_e32 v52, v56, v52
	v_mul_f32_e32 v53, v57, v53
	v_mul_f32_e32 v54, v58, v54
	v_mul_f32_e32 v55, v59, v55
	v_mul_f32_e32 v64, 0xbfb8aa3b, v64
	v_mul_f32_e32 v65, 0xbfb8aa3b, v65
	v_mul_f32_e32 v66, 0xbfb8aa3b, v66
	v_mul_f32_e32 v67, 0xbfb8aa3b, v67
	v_mul_f32_e32 v56, 0xbfb8aa3b, v56
	v_mul_f32_e32 v57, 0xbfb8aa3b, v57
	v_mul_f32_e32 v58, 0xbfb8aa3b, v58
	v_mul_f32_e32 v59, 0xbfb8aa3b, v59
	v_exp_f32_e32 v64, v64
	v_exp_f32_e32 v65, v65
	v_exp_f32_e32 v66, v66
	v_exp_f32_e32 v67, v67
	v_exp_f32_e32 v56, v56
	v_exp_f32_e32 v57, v57
	v_exp_f32_e32 v58, v58
	v_exp_f32_e32 v59, v59
	v_add_f32_e32 v64, 1.0, v64
	v_add_f32_e32 v65, 1.0, v65
	v_add_f32_e32 v66, 1.0, v66
	v_add_f32_e32 v67, 1.0, v67
	v_add_f32_e32 v56, 1.0, v56
	v_add_f32_e32 v57, 1.0, v57
	v_add_f32_e32 v58, 1.0, v58
	v_add_f32_e32 v59, 1.0, v59
	v_rcp_f32_e32 v64, v64
	v_rcp_f32_e32 v65, v65
	v_rcp_f32_e32 v66, v66
	v_rcp_f32_e32 v67, v67
	v_rcp_f32_e32 v56, v56
	v_rcp_f32_e32 v57, v57
	v_rcp_f32_e32 v58, v58
	v_rcp_f32_e32 v59, v59
	v_mul_f32_e32 v64, v60, v64
	v_mul_f32_e32 v65, v61, v65
	v_mul_f32_e32 v66, v62, v66
	v_mul_f32_e32 v67, v63, v67
	v_mul_f32_e32 v56, v52, v56
	v_mul_f32_e32 v57, v53, v57
	v_mul_f32_e32 v58, v54, v58
	v_mul_f32_e32 v59, v55, v59
	v_cvt_pk_bf16_f32 v64, v64, v65
	v_cvt_pk_bf16_f32 v65, v66, v67
	v_cvt_pk_bf16_f32 v66, v56, v57
	v_cvt_pk_bf16_f32 v67, v58, v59
	global_store_dwordx4 v188, v[64:67], s[28:29]
	v_mov_b32_e32 v232, v247
	v_pk_mul_f32 v[48:49], v[48:49], v[232:233] op_sel_hi:[1,0]
	v_pk_mul_f32 v[50:51], v[50:51], v[232:233] op_sel_hi:[1,0]
	v_pk_mul_f32 v[40:41], v[40:41], v[232:233] op_sel_hi:[1,0]
; __device__ __forceinline__ unsigned cvt_pk_bf16(float lo, float hi) { unsigned r; asm volatile("v_cvt_pk_bf16_f32 %0, %1, %2" : "=v"(r) : "v"(lo), "v"(hi)); return r; }
;     __device__ bool next(int i, Unit& u) const { return b.next(i, u); }
;     __device__ __forceinline__ void operator()(const f32x4 (&acc)[2][2][4][2], const Unit& u, int wr, int wc, int fr, int fq) const {
;     ...
;             for (int m = 0; m < 4; ++m) { const int row = row0 + ai * HALF + m * 16; const f32x4 q0 = *(const f32x4*)(ssq + (size_t)row * 16), q1 = *(const f32x4*)(ssq + (size_t)row * 16 + 4), q2 = *(const f32x4*)(ssq + (size_t)row * 16 + 8), q3 = *(const f32x4*)(ssq + (size_t)row * 16 + 12);
;                 const float rs = rsqrtf(((((q0[0] + q0[1]) + (q0[2] + q0[3])) + ((q1[0] + q1[1]) + (q1[2] + q1[3]))) + (((q2[0] + q2[1]) + (q2[2] + q2[3])) + ((q3[0] + q3[1]) + (q3[2] + q3[3])))) * (1.0f / 1024.0f) + 1e-6f);
;                 float a[8];
; #pragma unroll
;                 for (int n = 0; n < 2; ++n)
; #pragma unroll
;                     for (int j = 0; j < 4; ++j) { const float g = acc[ai][0][m][n][j] * rs, up = acc[ai][1][m][n][j] * rs; a[4 * n + j] = g * up * __builtin_amdgcn_rcpf(1.0f + __expf(-g)); }
;                 u32x4 w; w.x = cvt_pk_bf16(a[0], a[1]); w.y = cvt_pk_bf16(a[2], a[3]); w.z = cvt_pk_bf16(a[4], a[5]); w.w = cvt_pk_bf16(a[6], a[7]);
;                 *(u32x4*)(O + (size_t)row * ldc + col0) = w; }
; template <class Epi, class Sched, bool ALIGN_EPI = false, bool SP2 = false>
; __device__ __forceinline__ void gemm_phase(PG8_LAS unsigned char* lds, const Gemm g, const Sched& S, const Epi& E) {
;     ...
;         const bool has_next = S.next(ui + 1, nxt);
	v_pk_mul_f32 v[42:43], v[42:43], v[232:233] op_sel_hi:[1,0]
	v_pk_mul_f32 v[44:45], v[44:45], v[232:233] op_sel_hi:[1,0]
	v_pk_mul_f32 v[46:47], v[46:47], v[232:233] op_sel_hi:[1,0]
	v_pk_mul_f32 v[36:37], v[36:37], v[232:233] op_sel_hi:[1,0]
	v_pk_mul_f32 v[38:39], v[38:39], v[232:233] op_sel_hi:[1,0]
	v_mul_f32_e32 v44, v48, v44
	v_mul_f32_e32 v45, v49, v45
	v_mul_f32_e32 v46, v50, v46
	v_mul_f32_e32 v47, v51, v47
	v_mul_f32_e32 v36, v40, v36
	v_mul_f32_e32 v37, v41, v37
	v_mul_f32_e32 v38, v42, v38
	v_mul_f32_e32 v39, v43, v39
	v_mul_f32_e32 v48, 0xbfb8aa3b, v48
	v_mul_f32_e32 v49, 0xbfb8aa3b, v49
	v_mul_f32_e32 v50, 0xbfb8aa3b, v50
	v_mul_f32_e32 v51, 0xbfb8aa3b, v51
	v_mul_f32_e32 v40, 0xbfb8aa3b, v40
	v_mul_f32_e32 v41, 0xbfb8aa3b, v41
	v_mul_f32_e32 v42, 0xbfb8aa3b, v42
	v_mul_f32_e32 v43, 0xbfb8aa3b, v43
	v_exp_f32_e32 v48, v48
	v_exp_f32_e32 v49, v49
	v_exp_f32_e32 v50, v50
	v_exp_f32_e32 v51, v51
	v_exp_f32_e32 v40, v40
	v_exp_f32_e32 v41, v41
	v_exp_f32_e32 v42, v42
	v_exp_f32_e32 v43, v43
	v_add_f32_e32 v48, 1.0, v48
	v_add_f32_e32 v49, 1.0, v49
	v_add_f32_e32 v50, 1.0, v50
	v_add_f32_e32 v51, 1.0, v51
	v_add_f32_e32 v40, 1.0, v40
	v_add_f32_e32 v41, 1.0, v41
	v_add_f32_e32 v42, 1.0, v42
	v_add_f32_e32 v43, 1.0, v43
	v_rcp_f32_e32 v48, v48
	v_rcp_f32_e32 v49, v49
	v_rcp_f32_e32 v50, v50
	v_rcp_f32_e32 v51, v51
	v_rcp_f32_e32 v40, v40
	v_rcp_f32_e32 v41, v41
	v_rcp_f32_e32 v42, v42
	v_rcp_f32_e32 v43, v43
	v_mul_f32_e32 v48, v44, v48
	v_mul_f32_e32 v49, v45, v49
	v_mul_f32_e32 v50, v46, v50
	v_mul_f32_e32 v51, v47, v51
	v_mul_f32_e32 v40, v36, v40
	v_mul_f32_e32 v41, v37, v41
	v_mul_f32_e32 v42, v38, v42
	v_mul_f32_e32 v43, v39, v43
	v_cvt_pk_bf16_f32 v48, v48, v49
	v_cvt_pk_bf16_f32 v49, v50, v51
	v_cvt_pk_bf16_f32 v50, v40, v41
	v_cvt_pk_bf16_f32 v51, v42, v43
	global_store_dwordx4 v189, v[48:51], s[28:29]
	v_mov_b32_e32 v232, v248
	v_pk_mul_f32 v[32:33], v[32:33], v[232:233] op_sel_hi:[1,0]
	v_pk_mul_f32 v[34:35], v[34:35], v[232:233] op_sel_hi:[1,0]
	v_pk_mul_f32 v[24:25], v[24:25], v[232:233] op_sel_hi:[1,0]
	v_pk_mul_f32 v[26:27], v[26:27], v[232:233] op_sel_hi:[1,0]
	v_pk_mul_f32 v[28:29], v[28:29], v[232:233] op_sel_hi:[1,0]
	v_pk_mul_f32 v[30:31], v[30:31], v[232:233] op_sel_hi:[1,0]
	v_pk_mul_f32 v[20:21], v[20:21], v[232:233] op_sel_hi:[1,0]
	v_pk_mul_f32 v[22:23], v[22:23], v[232:233] op_sel_hi:[1,0]
	v_mul_f32_e32 v28, v32, v28
	v_mul_f32_e32 v29, v33, v29
	v_mul_f32_e32 v30, v34, v30
	v_mul_f32_e32 v31, v35, v31
	v_mul_f32_e32 v20, v24, v20
	v_mul_f32_e32 v21, v25, v21
	v_mul_f32_e32 v22, v26, v22
	v_mul_f32_e32 v23, v27, v23
	v_mul_f32_e32 v32, 0xbfb8aa3b, v32
	v_mul_f32_e32 v33, 0xbfb8aa3b, v33
	v_mul_f32_e32 v34, 0xbfb8aa3b, v34
	v_mul_f32_e32 v35, 0xbfb8aa3b, v35
	v_mul_f32_e32 v24, 0xbfb8aa3b, v24
	v_mul_f32_e32 v25, 0xbfb8aa3b, v25
	v_mul_f32_e32 v26, 0xbfb8aa3b, v26
	v_mul_f32_e32 v27, 0xbfb8aa3b, v27
	v_exp_f32_e32 v32, v32
	v_exp_f32_e32 v33, v33
	v_exp_f32_e32 v34, v34
	v_exp_f32_e32 v35, v35
	v_exp_f32_e32 v24, v24
	v_exp_f32_e32 v25, v25
	v_exp_f32_e32 v26, v26
	v_exp_f32_e32 v27, v27
	v_add_f32_e32 v32, 1.0, v32
	v_add_f32_e32 v33, 1.0, v33
	v_add_f32_e32 v34, 1.0, v34
	v_add_f32_e32 v35, 1.0, v35
	v_add_f32_e32 v24, 1.0, v24
	v_add_f32_e32 v25, 1.0, v25
	v_add_f32_e32 v26, 1.0, v26
	v_add_f32_e32 v27, 1.0, v27
	v_rcp_f32_e32 v32, v32
	v_rcp_f32_e32 v33, v33
	v_rcp_f32_e32 v34, v34
	v_rcp_f32_e32 v35, v35
	v_rcp_f32_e32 v24, v24
	v_rcp_f32_e32 v25, v25
	v_rcp_f32_e32 v26, v26
	v_rcp_f32_e32 v27, v27
	v_mul_f32_e32 v32, v28, v32
	v_mul_f32_e32 v33, v29, v33
	v_mul_f32_e32 v34, v30, v34
	v_mul_f32_e32 v35, v31, v35
	v_mul_f32_e32 v24, v20, v24
	v_mul_f32_e32 v25, v21, v25
	v_mul_f32_e32 v26, v22, v26
	v_mul_f32_e32 v27, v23, v27
	v_cvt_pk_bf16_f32 v32, v32, v33
	v_cvt_pk_bf16_f32 v33, v34, v35
	v_cvt_pk_bf16_f32 v34, v24, v25
	v_cvt_pk_bf16_f32 v35, v26, v27
	global_store_dwordx4 v190, v[32:35], s[28:29]
	v_mov_b32_e32 v232, v249
	v_pk_mul_f32 v[16:17], v[16:17], v[232:233] op_sel_hi:[1,0]
	v_pk_mul_f32 v[18:19], v[18:19], v[232:233] op_sel_hi:[1,0]
	v_pk_mul_f32 v[8:9], v[8:9], v[232:233] op_sel_hi:[1,0]
	v_pk_mul_f32 v[10:11], v[10:11], v[232:233] op_sel_hi:[1,0]
	v_pk_mul_f32 v[12:13], v[12:13], v[232:233] op_sel_hi:[1,0]
	v_pk_mul_f32 v[14:15], v[14:15], v[232:233] op_sel_hi:[1,0]
	v_pk_mul_f32 v[4:5], v[4:5], v[232:233] op_sel_hi:[1,0]
	v_pk_mul_f32 v[6:7], v[6:7], v[232:233] op_sel_hi:[1,0]
	v_mul_f32_e32 v12, v16, v12
	v_mul_f32_e32 v13, v17, v13
	v_mul_f32_e32 v14, v18, v14
	v_mul_f32_e32 v15, v19, v15
	v_mul_f32_e32 v4, v8, v4
	v_mul_f32_e32 v5, v9, v5
	v_mul_f32_e32 v6, v10, v6
	v_mul_f32_e32 v7, v11, v7
	v_mul_f32_e32 v16, 0xbfb8aa3b, v16
	v_mul_f32_e32 v17, 0xbfb8aa3b, v17
	v_mul_f32_e32 v18, 0xbfb8aa3b, v18
	v_mul_f32_e32 v19, 0xbfb8aa3b, v19
	v_mul_f32_e32 v8, 0xbfb8aa3b, v8
	v_mul_f32_e32 v9, 0xbfb8aa3b, v9
	v_mul_f32_e32 v10, 0xbfb8aa3b, v10
	v_mul_f32_e32 v11, 0xbfb8aa3b, v11
	v_exp_f32_e32 v16, v16
	v_exp_f32_e32 v17, v17
	v_exp_f32_e32 v18, v18
	v_exp_f32_e32 v19, v19
	v_exp_f32_e32 v8, v8
	v_exp_f32_e32 v9, v9
	v_exp_f32_e32 v10, v10
	v_exp_f32_e32 v11, v11
	v_add_f32_e32 v16, 1.0, v16
	v_add_f32_e32 v17, 1.0, v17
	v_add_f32_e32 v18, 1.0, v18
	v_add_f32_e32 v19, 1.0, v19
	v_add_f32_e32 v8, 1.0, v8
	v_add_f32_e32 v9, 1.0, v9
	v_add_f32_e32 v10, 1.0, v10
	v_add_f32_e32 v11, 1.0, v11
	v_rcp_f32_e32 v16, v16
	v_rcp_f32_e32 v17, v17
	v_rcp_f32_e32 v18, v18
	v_rcp_f32_e32 v19, v19
	v_rcp_f32_e32 v8, v8
	v_rcp_f32_e32 v9, v9
	v_rcp_f32_e32 v10, v10
	v_rcp_f32_e32 v11, v11
	v_mul_f32_e32 v16, v12, v16
	v_mul_f32_e32 v17, v13, v17
	v_mul_f32_e32 v18, v14, v18
	v_mul_f32_e32 v19, v15, v19
	v_mul_f32_e32 v8, v4, v8
	v_mul_f32_e32 v9, v5, v9
	v_mul_f32_e32 v10, v6, v10
	v_mul_f32_e32 v11, v7, v11
	v_cvt_pk_bf16_f32 v16, v16, v17
	v_cvt_pk_bf16_f32 v17, v18, v19
	v_cvt_pk_bf16_f32 v18, v8, v9
	v_cvt_pk_bf16_f32 v19, v10, v11
	global_store_dwordx4 v191, v[16:19], s[28:29]
	s_and_b64 vcc, exec, s[2:3]
	s_cbranch_vccz .Lsw_nonext2
;     __device__ __forceinline__ void operator()(const f32x4 (&acc)[2][2][4][2], const Unit& u, int wr, int wc, int fr, int fq) const {
;     ...
;             for (int m = 0; m < 4; ++m) { const int row = row0 + ai * HALF + m * 16; const f32x4 q0 = *(const f32x4*)(ssq + (size_t)row * 16), q1 = *(const f32x4*)(ssq + (size_t)row * 16 + 4), q2 = *(const f32x4*)(ssq + (size_t)row * 16 + 8), q3 = *(const f32x4*)(ssq + (size_t)row * 16 + 12);
;                 const float rs = rsqrtf(((((q0[0] + q0[1]) + (q0[2] + q0[3])) + ((q1[0] + q1[1]) + (q1[2] + q1[3]))) + (((q2[0] + q2[1]) + (q2[2] + q2[3])) + ((q3[0] + q3[1]) + (q3[2] + q3[3])))) * (1.0f / 1024.0f) + 1e-6f);
	s_waitcnt vmcnt(15)
	v_add_f32_e32 v154, v154, v155
	v_add_f32_e32 v194, v152, v153
	v_add_f32_e32 v194, v194, v154
	s_waitcnt vmcnt(14)
	v_add_f32_e32 v158, v158, v159
	v_add_f32_e32 v195, v156, v157
	v_add_f32_e32 v195, v195, v158
	s_waitcnt vmcnt(13)
	v_add_f32_e32 v162, v162, v163
	v_add_f32_e32 v196, v160, v161
	v_add_f32_e32 v196, v196, v162
	s_waitcnt vmcnt(12)
	v_add_f32_e32 v166, v166, v167
	v_add_f32_e32 v197, v164, v165
	v_add_f32_e32 v197, v197, v166
	s_waitcnt vmcnt(11)
	v_add_f32_e32 v170, v170, v171
	v_add_f32_e32 v204, v168, v169
	v_add_f32_e32 v204, v204, v170
	s_waitcnt vmcnt(10)
	v_add_f32_e32 v174, v174, v175
	v_add_f32_e32 v205, v172, v173
	v_add_f32_e32 v205, v205, v174
	s_waitcnt vmcnt(9)
	v_add_f32_e32 v178, v178, v179
	v_add_f32_e32 v206, v176, v177
	v_add_f32_e32 v206, v206, v178
	s_waitcnt vmcnt(8)
	v_add_f32_e32 v182, v182, v183
	v_add_f32_e32 v207, v180, v181
	v_add_f32_e32 v207, v207, v182
	ds_bpermute_b32 v220, v228, v194
	ds_bpermute_b32 v221, v228, v195
	ds_bpermute_b32 v222, v228, v196
	ds_bpermute_b32 v223, v228, v197
	ds_bpermute_b32 v224, v228, v204
	ds_bpermute_b32 v225, v228, v205
	ds_bpermute_b32 v226, v228, v206
	ds_bpermute_b32 v227, v228, v207
	s_waitcnt lgkmcnt(7)
	v_add_f32_e32 v194, v194, v220
	s_waitcnt lgkmcnt(6)
	v_add_f32_e32 v195, v195, v221
	s_waitcnt lgkmcnt(5)
	v_add_f32_e32 v196, v196, v222
	s_waitcnt lgkmcnt(4)
	v_add_f32_e32 v197, v197, v223
	s_waitcnt lgkmcnt(3)
	v_add_f32_e32 v204, v204, v224
	s_waitcnt lgkmcnt(2)
	v_add_f32_e32 v205, v205, v225
	s_waitcnt lgkmcnt(1)
	v_add_f32_e32 v206, v206, v226
	s_waitcnt lgkmcnt(0)
	v_add_f32_e32 v207, v207, v227
	ds_bpermute_b32 v220, v229, v194
	ds_bpermute_b32 v221, v229, v195
	ds_bpermute_b32 v222, v229, v196
	ds_bpermute_b32 v223, v229, v197
	ds_bpermute_b32 v224, v229, v204
	ds_bpermute_b32 v225, v229, v205
	ds_bpermute_b32 v226, v229, v206
	ds_bpermute_b32 v227, v229, v207
	s_waitcnt lgkmcnt(7)
	v_add_f32_e32 v194, v194, v220
	s_waitcnt lgkmcnt(6)
	v_add_f32_e32 v195, v195, v221
	s_waitcnt lgkmcnt(5)
	v_add_f32_e32 v196, v196, v222
	s_waitcnt lgkmcnt(4)
	v_add_f32_e32 v197, v197, v223
	s_waitcnt lgkmcnt(3)
	v_add_f32_e32 v204, v204, v224
	s_waitcnt lgkmcnt(2)
	v_add_f32_e32 v205, v205, v225
	s_waitcnt lgkmcnt(1)
	v_add_f32_e32 v206, v206, v226
	s_waitcnt lgkmcnt(0)
	v_add_f32_e32 v207, v207, v227
	v_fmamk_f32 v194, v194, 0x3a800000, v208
	v_fmamk_f32 v195, v195, 0x3a800000, v208
	v_fmamk_f32 v196, v196, 0x3a800000, v208
	v_fmamk_f32 v197, v197, 0x3a800000, v208
	v_fmamk_f32 v204, v204, 0x3a800000, v208
	v_fmamk_f32 v205, v205, 0x3a800000, v208
	v_fmamk_f32 v206, v206, 0x3a800000, v208
	v_fmamk_f32 v207, v207, 0x3a800000, v208
	v_rsq_f32_e32 v242, v194
	v_rsq_f32_e32 v243, v195
	v_rsq_f32_e32 v244, v196
	v_rsq_f32_e32 v245, v197
	v_rsq_f32_e32 v246, v204
	v_rsq_f32_e32 v247, v205
	v_rsq_f32_e32 v248, v206
	v_rsq_f32_e32 v249, v207
.Lsw_nonext2:
	s_mov_b32 s23, 0x800000
	v_readlane_b32 s60, v253, 3
	s_mov_b32 s99, 0x800000
	v_readlane_b32 s61, v253, 4
	v_readlane_b32 s62, v253, 5
	v_readlane_b32 s63, v253, 6
	s_andn2_b64 vcc, exec, s[2:3]
	s_mov_b64 s[28:29], -1
	s_cbranch_vccnz .LBB0_603
	s_andn2_b64 vcc, exec, s[14:15]
	s_cbranch_vccnz .LBB0_602
	s_barrier
	s_branch .LBB0_602

;     __device__ __forceinline__ void operator()(const f32x4 (&acc)[2][2][4][2], const Unit& u, int wr, int wc, int fr, int fq) const {
;         const int row0 = u.pm * BM + wr * 64 + fr, col0 = u.pn * BM + wc * 32 + 8 * fq;
; #pragma unroll
;         for (int ai = 0; ai < 2; ++ai)
; #pragma unroll
;             for (int m = 0; m < 4; ++m) { const int row = row0 + ai * HALF + m * 16; const f32x4 q0 = *(const f32x4*)(ssq + (size_t)row * 16), q1 = *(const f32x4*)(ssq + (size_t)row * 16 + 4), q2 = *(const f32x4*)(ssq + (size_t)row * 16 + 8), q3 = *(const f32x4*)(ssq + (size_t)row * 16 + 12);
;                 const float rs = rsqrtf(((((q0[0] + q0[1]) + (q0[2] + q0[3])) + ((q1[0] + q1[1]) + (q1[2] + q1[3]))) + (((q2[0] + q2[1]) + (q2[2] + q2[3])) + ((q3[0] + q3[1]) + (q3[2] + q3[3])))) * (1.0f / 1024.0f) + 1e-6f);
.LBB0_688:
	v_xor_b32_e32 v228, 16, v214
	v_lshlrev_b32_e32 v228, 2, v228
	v_xor_b32_e32 v229, 32, v214
	v_lshlrev_b32_e32 v229, 2, v229
	s_cmp_eq_u32 s64, 1
	s_cbranch_scc0 .Lsc_have_rs
	v_lshl_add_u32 v190, s40, 8, v146
	v_and_b32_e32 v191, 24, v148
	v_lshlrev_b32_e32 v191, 1, v191
	v_lshl_add_u32 v191, v190, 6, v191
	v_add_u32_e32 v230, 0x2000, v191
	global_load_dwordx4 v[150:153], v191, s[22:23]
	global_load_dwordx4 v[154:157], v191, s[22:23] offset:1024
	global_load_dwordx4 v[158:161], v191, s[22:23] offset:2048
	global_load_dwordx4 v[162:165], v191, s[22:23] offset:3072
	global_load_dwordx4 v[166:169], v230, s[22:23]
	global_load_dwordx4 v[170:173], v230, s[22:23] offset:1024
	global_load_dwordx4 v[174:177], v230, s[22:23] offset:2048
	global_load_dwordx4 v[178:181], v230, s[22:23] offset:3072
	s_waitcnt vmcnt(7)
	v_add_f32_e32 v152, v152, v153
	v_add_f32_e32 v192, v150, v151
	v_add_f32_e32 v192, v192, v152
	s_waitcnt vmcnt(6)
	v_add_f32_e32 v156, v156, v157
	v_add_f32_e32 v193, v154, v155
	v_add_f32_e32 v193, v193, v156
	s_waitcnt vmcnt(5)
	v_add_f32_e32 v160, v160, v161
	v_add_f32_e32 v194, v158, v159
	v_add_f32_e32 v194, v194, v160
	s_waitcnt vmcnt(4)
	v_add_f32_e32 v164, v164, v165
	v_add_f32_e32 v195, v162, v163
	v_add_f32_e32 v195, v195, v164
	s_waitcnt vmcnt(3)
	v_add_f32_e32 v168, v168, v169
	v_add_f32_e32 v196, v166, v167
	v_add_f32_e32 v196, v196, v168
	s_waitcnt vmcnt(2)
	v_add_f32_e32 v172, v172, v173
	v_add_f32_e32 v197, v170, v171
	v_add_f32_e32 v197, v197, v172
	s_waitcnt vmcnt(1)
	v_add_f32_e32 v176, v176, v177
	v_add_f32_e32 v204, v174, v175
	v_add_f32_e32 v204, v204, v176
	s_waitcnt vmcnt(0)
	v_add_f32_e32 v180, v180, v181
	v_add_f32_e32 v205, v178, v179
	v_add_f32_e32 v205, v205, v180
	ds_bpermute_b32 v220, v228, v192
	ds_bpermute_b32 v221, v228, v193
	ds_bpermute_b32 v222, v228, v194
	ds_bpermute_b32 v223, v228, v195
	ds_bpermute_b32 v224, v228, v196
	ds_bpermute_b32 v225, v228, v197
	ds_bpermute_b32 v226, v228, v204
	ds_bpermute_b32 v227, v228, v205
	s_waitcnt lgkmcnt(7)
	v_add_f32_e32 v192, v192, v220
	s_waitcnt lgkmcnt(6)
	v_add_f32_e32 v193, v193, v221
	s_waitcnt lgkmcnt(5)
	v_add_f32_e32 v194, v194, v222
	s_waitcnt lgkmcnt(4)
	v_add_f32_e32 v195, v195, v223
	s_waitcnt lgkmcnt(3)
	v_add_f32_e32 v196, v196, v224
	s_waitcnt lgkmcnt(2)
	v_add_f32_e32 v197, v197, v225
	s_waitcnt lgkmcnt(1)
	v_add_f32_e32 v204, v204, v226
	s_waitcnt lgkmcnt(0)
	v_add_f32_e32 v205, v205, v227
	ds_bpermute_b32 v220, v229, v192
	ds_bpermute_b32 v221, v229, v193
	ds_bpermute_b32 v222, v229, v194
	ds_bpermute_b32 v223, v229, v195
	ds_bpermute_b32 v224, v229, v196
	ds_bpermute_b32 v225, v229, v197
	ds_bpermute_b32 v226, v229, v204
	ds_bpermute_b32 v227, v229, v205
	s_waitcnt lgkmcnt(7)
	v_add_f32_e32 v192, v192, v220
	s_waitcnt lgkmcnt(6)
	v_add_f32_e32 v193, v193, v221
	s_waitcnt lgkmcnt(5)
	v_add_f32_e32 v194, v194, v222
	s_waitcnt lgkmcnt(4)
	v_add_f32_e32 v195, v195, v223
	s_waitcnt lgkmcnt(3)
	v_add_f32_e32 v196, v196, v224
	s_waitcnt lgkmcnt(2)
	v_add_f32_e32 v197, v197, v225
	s_waitcnt lgkmcnt(1)
	v_add_f32_e32 v204, v204, v226
	s_waitcnt lgkmcnt(0)
	v_add_f32_e32 v205, v205, v227
	v_fmamk_f32 v192, v192, 0x3a800000, v208
	v_fmamk_f32 v193, v193, 0x3a800000, v208
	v_fmamk_f32 v194, v194, 0x3a800000, v208
	v_fmamk_f32 v195, v195, 0x3a800000, v208
	v_fmamk_f32 v196, v196, 0x3a800000, v208
	v_fmamk_f32 v197, v197, 0x3a800000, v208
	v_fmamk_f32 v204, v204, 0x3a800000, v208
	v_fmamk_f32 v205, v205, 0x3a800000, v208
	v_rsq_f32_e32 v242, v192
	v_rsq_f32_e32 v243, v193
	v_rsq_f32_e32 v244, v194
	v_rsq_f32_e32 v245, v195
	v_rsq_f32_e32 v246, v196
	v_rsq_f32_e32 v247, v197
	v_rsq_f32_e32 v248, v204
	v_rsq_f32_e32 v249, v205
.Lsc_have_rs:
	s_and_b64 vcc, exec, s[2:3]
	s_cbranch_vccz .Lsc_nonext1
	v_lshl_add_u32 v190, s34, 8, v146
	v_and_b32_e32 v191, 24, v148
	v_lshlrev_b32_e32 v191, 1, v191
	v_lshl_add_u32 v191, v190, 6, v191
	v_add_u32_e32 v230, 0x2000, v191
	global_load_dwordx4 v[150:153], v191, s[22:23]
	global_load_dwordx4 v[154:157], v191, s[22:23] offset:1024
	global_load_dwordx4 v[158:161], v191, s[22:23] offset:2048
	global_load_dwordx4 v[162:165], v191, s[22:23] offset:3072
	global_load_dwordx4 v[166:169], v230, s[22:23]
	global_load_dwordx4 v[170:173], v230, s[22:23] offset:1024
	global_load_dwordx4 v[174:177], v230, s[22:23] offset:2048
	global_load_dwordx4 v[178:181], v230, s[22:23] offset:3072
; __device__ __forceinline__ unsigned cvt_pk_bf16(float lo, float hi) { unsigned r; asm volatile("v_cvt_pk_bf16_f32 %0, %1, %2" : "=v"(r) : "v"(lo), "v"(hi)); return r; }
;     __device__ __forceinline__ void operator()(const f32x4 (&acc)[2][2][4][2], const Unit& u, int wr, int wc, int fr, int fq) const {
;     ...
;                 bf16_t* rowp = O + (size_t)row * ldc + col0;
; #pragma unroll
;                 for (int bj = 0; bj < 2; ++bj) { const f32x4 v0 = acc[ai][bj][m][0] * rs, v1 = acc[ai][bj][m][1] * rs;
;                     u32x4 w; w.x = cvt_pk_bf16(v0[0], v0[1]); w.y = cvt_pk_bf16(v0[2], v0[3]); w.z = cvt_pk_bf16(v1[0], v1[1]); w.w = cvt_pk_bf16(v1[2], v1[3]);
;                     *(u32x4*)(rowp + bj * HALF) = w; } }
.Lsc_nonext1:
	v_lshl_add_u32 v190, s40, 8, v146
	s_lshl_b32 s31, s50, 1
	v_lshl_or_b32 v231, s41, 8, v148
	v_lshlrev_b32_e32 v231, 1, v231
	v_mad_u32_u24 v182, v190, s31, v231
	s_lshl_b32 s99, s50, 5
	v_add_u32_e32 v183, s99, v182
	v_add_u32_e32 v184, s99, v183
	v_add_u32_e32 v185, s99, v184
	s_lshl_b32 s99, s50, 8
	v_add_u32_e32 v186, s99, v182
	v_add_u32_e32 v187, s99, v183
	v_add_u32_e32 v188, s99, v184
	v_add_u32_e32 v189, s99, v185
	v_mov_b32_e32 v232, v242
	v_pk_mul_f32 v[128:129], v[128:129], v[232:233] op_sel_hi:[1,0]
	v_pk_mul_f32 v[130:131], v[130:131], v[232:233] op_sel_hi:[1,0]
	v_pk_mul_f32 v[124:125], v[124:125], v[232:233] op_sel_hi:[1,0]
	v_pk_mul_f32 v[126:127], v[126:127], v[232:233] op_sel_hi:[1,0]
	v_cvt_pk_bf16_f32 v128, v128, v129
	v_cvt_pk_bf16_f32 v129, v130, v131
	v_cvt_pk_bf16_f32 v130, v124, v125
	v_cvt_pk_bf16_f32 v131, v126, v127
	global_store_dwordx4 v182, v[128:131], s[18:19]
	v_pk_mul_f32 v[120:121], v[120:121], v[232:233] op_sel_hi:[1,0]
	v_pk_mul_f32 v[122:123], v[122:123], v[232:233] op_sel_hi:[1,0]
	v_pk_mul_f32 v[116:117], v[116:117], v[232:233] op_sel_hi:[1,0]
	v_pk_mul_f32 v[118:119], v[118:119], v[232:233] op_sel_hi:[1,0]
	v_cvt_pk_bf16_f32 v120, v120, v121
	v_cvt_pk_bf16_f32 v121, v122, v123
	v_cvt_pk_bf16_f32 v122, v116, v117
	v_cvt_pk_bf16_f32 v123, v118, v119
	global_store_dwordx4 v182, v[120:123], s[18:19] offset:256
	v_mov_b32_e32 v232, v243
	v_pk_mul_f32 v[112:113], v[112:113], v[232:233] op_sel_hi:[1,0]
	v_pk_mul_f32 v[114:115], v[114:115], v[232:233] op_sel_hi:[1,0]
	v_pk_mul_f32 v[108:109], v[108:109], v[232:233] op_sel_hi:[1,0]
	v_pk_mul_f32 v[110:111], v[110:111], v[232:233] op_sel_hi:[1,0]
	v_cvt_pk_bf16_f32 v112, v112, v113
	v_cvt_pk_bf16_f32 v113, v114, v115
	v_cvt_pk_bf16_f32 v114, v108, v109
	v_cvt_pk_bf16_f32 v115, v110, v111
	global_store_dwordx4 v183, v[112:115], s[18:19]
	v_pk_mul_f32 v[104:105], v[104:105], v[232:233] op_sel_hi:[1,0]
	v_pk_mul_f32 v[106:107], v[106:107], v[232:233] op_sel_hi:[1,0]
	v_pk_mul_f32 v[100:101], v[100:101], v[232:233] op_sel_hi:[1,0]
	v_pk_mul_f32 v[102:103], v[102:103], v[232:233] op_sel_hi:[1,0]
	v_cvt_pk_bf16_f32 v104, v104, v105
	v_cvt_pk_bf16_f32 v105, v106, v107
	v_cvt_pk_bf16_f32 v106, v100, v101
	v_cvt_pk_bf16_f32 v107, v102, v103
	global_store_dwordx4 v183, v[104:107], s[18:19] offset:256
	v_mov_b32_e32 v232, v244
	v_pk_mul_f32 v[96:97], v[96:97], v[232:233] op_sel_hi:[1,0]
	v_pk_mul_f32 v[98:99], v[98:99], v[232:233] op_sel_hi:[1,0]
	v_pk_mul_f32 v[92:93], v[92:93], v[232:233] op_sel_hi:[1,0]
	v_pk_mul_f32 v[94:95], v[94:95], v[232:233] op_sel_hi:[1,0]
	v_cvt_pk_bf16_f32 v96, v96, v97
	v_cvt_pk_bf16_f32 v97, v98, v99
	v_cvt_pk_bf16_f32 v98, v92, v93
	v_cvt_pk_bf16_f32 v99, v94, v95
	global_store_dwordx4 v184, v[96:99], s[18:19]
	v_pk_mul_f32 v[88:89], v[88:89], v[232:233] op_sel_hi:[1,0]
	v_pk_mul_f32 v[90:91], v[90:91], v[232:233] op_sel_hi:[1,0]
	v_pk_mul_f32 v[84:85], v[84:85], v[232:233] op_sel_hi:[1,0]
	v_pk_mul_f32 v[86:87], v[86:87], v[232:233] op_sel_hi:[1,0]
	v_cvt_pk_bf16_f32 v88, v88, v89
	v_cvt_pk_bf16_f32 v89, v90, v91
	v_cvt_pk_bf16_f32 v90, v84, v85
	v_cvt_pk_bf16_f32 v91, v86, v87
	global_store_dwordx4 v184, v[88:91], s[18:19] offset:256
	v_mov_b32_e32 v232, v245
	v_pk_mul_f32 v[80:81], v[80:81], v[232:233] op_sel_hi:[1,0]
	v_pk_mul_f32 v[82:83], v[82:83], v[232:233] op_sel_hi:[1,0]
	v_pk_mul_f32 v[76:77], v[76:77], v[232:233] op_sel_hi:[1,0]
	v_pk_mul_f32 v[78:79], v[78:79], v[232:233] op_sel_hi:[1,0]
	v_cvt_pk_bf16_f32 v80, v80, v81
	v_cvt_pk_bf16_f32 v81, v82, v83
	v_cvt_pk_bf16_f32 v82, v76, v77
	v_cvt_pk_bf16_f32 v83, v78, v79
	global_store_dwordx4 v185, v[80:83], s[18:19]
	v_pk_mul_f32 v[72:73], v[72:73], v[232:233] op_sel_hi:[1,0]
	v_pk_mul_f32 v[74:75], v[74:75], v[232:233] op_sel_hi:[1,0]
	v_pk_mul_f32 v[68:69], v[68:69], v[232:233] op_sel_hi:[1,0]
	v_pk_mul_f32 v[70:71], v[70:71], v[232:233] op_sel_hi:[1,0]
	v_cvt_pk_bf16_f32 v72, v72, v73
	v_cvt_pk_bf16_f32 v73, v74, v75
	v_cvt_pk_bf16_f32 v74, v68, v69
	v_cvt_pk_bf16_f32 v75, v70, v71
	global_store_dwordx4 v185, v[72:75], s[18:19] offset:256
	v_mov_b32_e32 v232, v246
	v_pk_mul_f32 v[64:65], v[64:65], v[232:233] op_sel_hi:[1,0]
	v_pk_mul_f32 v[66:67], v[66:67], v[232:233] op_sel_hi:[1,0]
	v_pk_mul_f32 v[60:61], v[60:61], v[232:233] op_sel_hi:[1,0]
	v_pk_mul_f32 v[62:63], v[62:63], v[232:233] op_sel_hi:[1,0]
	v_cvt_pk_bf16_f32 v64, v64, v65
	v_cvt_pk_bf16_f32 v65, v66, v67
	v_cvt_pk_bf16_f32 v66, v60, v61
	v_cvt_pk_bf16_f32 v67, v62, v63
	global_store_dwordx4 v186, v[64:67], s[18:19]
	v_pk_mul_f32 v[56:57], v[56:57], v[232:233] op_sel_hi:[1,0]
	v_pk_mul_f32 v[58:59], v[58:59], v[232:233] op_sel_hi:[1,0]
	v_pk_mul_f32 v[52:53], v[52:53], v[232:233] op_sel_hi:[1,0]
	v_pk_mul_f32 v[54:55], v[54:55], v[232:233] op_sel_hi:[1,0]
	v_cvt_pk_bf16_f32 v56, v56, v57
	v_cvt_pk_bf16_f32 v57, v58, v59
	v_cvt_pk_bf16_f32 v58, v52, v53
	v_cvt_pk_bf16_f32 v59, v54, v55
	global_store_dwordx4 v186, v[56:59], s[18:19] offset:256
	v_mov_b32_e32 v232, v247
	v_pk_mul_f32 v[48:49], v[48:49], v[232:233] op_sel_hi:[1,0]
	v_pk_mul_f32 v[50:51], v[50:51], v[232:233] op_sel_hi:[1,0]
	v_pk_mul_f32 v[44:45], v[44:45], v[232:233] op_sel_hi:[1,0]
	v_pk_mul_f32 v[46:47], v[46:47], v[232:233] op_sel_hi:[1,0]
	v_cvt_pk_bf16_f32 v48, v48, v49
	v_cvt_pk_bf16_f32 v49, v50, v51
	v_cvt_pk_bf16_f32 v50, v44, v45
	v_cvt_pk_bf16_f32 v51, v46, v47
	global_store_dwordx4 v187, v[48:51], s[18:19]
; __device__ __forceinline__ unsigned cvt_pk_bf16(float lo, float hi) { unsigned r; asm volatile("v_cvt_pk_bf16_f32 %0, %1, %2" : "=v"(r) : "v"(lo), "v"(hi)); return r; }
;     __device__ __forceinline__ void operator()(const f32x4 (&acc)[2][2][4][2], const Unit& u, int wr, int wc, int fr, int fq) const {
;     ...
;             for (int m = 0; m < 4; ++m) { const int row = row0 + ai * HALF + m * 16; const f32x4 q0 = *(const f32x4*)(ssq + (size_t)row * 16), q1 = *(const f32x4*)(ssq + (size_t)row * 16 + 4), q2 = *(const f32x4*)(ssq + (size_t)row * 16 + 8), q3 = *(const f32x4*)(ssq + (size_t)row * 16 + 12);
;                 const float rs = rsqrtf(((((q0[0] + q0[1]) + (q0[2] + q0[3])) + ((q1[0] + q1[1]) + (q1[2] + q1[3]))) + (((q2[0] + q2[1]) + (q2[2] + q2[3])) + ((q3[0] + q3[1]) + (q3[2] + q3[3])))) * (1.0f / 1024.0f) + 1e-6f);
;     ...
;                 for (int bj = 0; bj < 2; ++bj) { const f32x4 v0 = acc[ai][bj][m][0] * rs, v1 = acc[ai][bj][m][1] * rs;
;                     u32x4 w; w.x = cvt_pk_bf16(v0[0], v0[1]); w.y = cvt_pk_bf16(v0[2], v0[3]); w.z = cvt_pk_bf16(v1[0], v1[1]); w.w = cvt_pk_bf16(v1[2], v1[3]);
;                     *(u32x4*)(rowp + bj * HALF) = w; } }
	v_pk_mul_f32 v[40:41], v[40:41], v[232:233] op_sel_hi:[1,0]
	v_pk_mul_f32 v[42:43], v[42:43], v[232:233] op_sel_hi:[1,0]
	v_pk_mul_f32 v[36:37], v[36:37], v[232:233] op_sel_hi:[1,0]
	v_pk_mul_f32 v[38:39], v[38:39], v[232:233] op_sel_hi:[1,0]
	v_cvt_pk_bf16_f32 v40, v40, v41
	v_cvt_pk_bf16_f32 v41, v42, v43
	v_cvt_pk_bf16_f32 v42, v36, v37
	v_cvt_pk_bf16_f32 v43, v38, v39
	global_store_dwordx4 v187, v[40:43], s[18:19] offset:256
	v_mov_b32_e32 v232, v248
	v_pk_mul_f32 v[32:33], v[32:33], v[232:233] op_sel_hi:[1,0]
	v_pk_mul_f32 v[34:35], v[34:35], v[232:233] op_sel_hi:[1,0]
	v_pk_mul_f32 v[28:29], v[28:29], v[232:233] op_sel_hi:[1,0]
	v_pk_mul_f32 v[30:31], v[30:31], v[232:233] op_sel_hi:[1,0]
	v_cvt_pk_bf16_f32 v32, v32, v33
	v_cvt_pk_bf16_f32 v33, v34, v35
	v_cvt_pk_bf16_f32 v34, v28, v29
	v_cvt_pk_bf16_f32 v35, v30, v31
	global_store_dwordx4 v188, v[32:35], s[18:19]
	v_pk_mul_f32 v[24:25], v[24:25], v[232:233] op_sel_hi:[1,0]
	v_pk_mul_f32 v[26:27], v[26:27], v[232:233] op_sel_hi:[1,0]
	v_pk_mul_f32 v[20:21], v[20:21], v[232:233] op_sel_hi:[1,0]
	v_pk_mul_f32 v[22:23], v[22:23], v[232:233] op_sel_hi:[1,0]
	v_cvt_pk_bf16_f32 v24, v24, v25
	v_cvt_pk_bf16_f32 v25, v26, v27
	v_cvt_pk_bf16_f32 v26, v20, v21
	v_cvt_pk_bf16_f32 v27, v22, v23
	global_store_dwordx4 v188, v[24:27], s[18:19] offset:256
	v_mov_b32_e32 v232, v249
	v_pk_mul_f32 v[16:17], v[16:17], v[232:233] op_sel_hi:[1,0]
	v_pk_mul_f32 v[18:19], v[18:19], v[232:233] op_sel_hi:[1,0]
	v_pk_mul_f32 v[12:13], v[12:13], v[232:233] op_sel_hi:[1,0]
	v_pk_mul_f32 v[14:15], v[14:15], v[232:233] op_sel_hi:[1,0]
	v_cvt_pk_bf16_f32 v16, v16, v17
	v_cvt_pk_bf16_f32 v17, v18, v19
	v_cvt_pk_bf16_f32 v18, v12, v13
	v_cvt_pk_bf16_f32 v19, v14, v15
	global_store_dwordx4 v189, v[16:19], s[18:19]
	v_pk_mul_f32 v[8:9], v[8:9], v[232:233] op_sel_hi:[1,0]
	v_pk_mul_f32 v[10:11], v[10:11], v[232:233] op_sel_hi:[1,0]
	v_pk_mul_f32 v[4:5], v[4:5], v[232:233] op_sel_hi:[1,0]
	v_pk_mul_f32 v[6:7], v[6:7], v[232:233] op_sel_hi:[1,0]
	v_cvt_pk_bf16_f32 v8, v8, v9
	v_cvt_pk_bf16_f32 v9, v10, v11
	v_cvt_pk_bf16_f32 v10, v4, v5
	v_cvt_pk_bf16_f32 v11, v6, v7
	global_store_dwordx4 v189, v[8:11], s[18:19] offset:256
	s_and_b64 vcc, exec, s[2:3]
	s_cbranch_vccz .Lsc_nonext2
	s_waitcnt vmcnt(23)
	v_add_f32_e32 v152, v152, v153
	v_add_f32_e32 v192, v150, v151
	v_add_f32_e32 v192, v192, v152
	s_waitcnt vmcnt(22)
	v_add_f32_e32 v156, v156, v157
	v_add_f32_e32 v193, v154, v155
	v_add_f32_e32 v193, v193, v156
	s_waitcnt vmcnt(21)
	v_add_f32_e32 v160, v160, v161
	v_add_f32_e32 v194, v158, v159
	v_add_f32_e32 v194, v194, v160
	s_waitcnt vmcnt(20)
	v_add_f32_e32 v164, v164, v165
	v_add_f32_e32 v195, v162, v163
	v_add_f32_e32 v195, v195, v164
	s_waitcnt vmcnt(19)
	v_add_f32_e32 v168, v168, v169
	v_add_f32_e32 v196, v166, v167
	v_add_f32_e32 v196, v196, v168
	s_waitcnt vmcnt(18)
	v_add_f32_e32 v172, v172, v173
	v_add_f32_e32 v197, v170, v171
	v_add_f32_e32 v197, v197, v172
	s_waitcnt vmcnt(17)
	v_add_f32_e32 v176, v176, v177
	v_add_f32_e32 v204, v174, v175
	v_add_f32_e32 v204, v204, v176
	s_waitcnt vmcnt(16)
	v_add_f32_e32 v180, v180, v181
	v_add_f32_e32 v205, v178, v179
	v_add_f32_e32 v205, v205, v180
	ds_bpermute_b32 v220, v228, v192
	ds_bpermute_b32 v221, v228, v193
	ds_bpermute_b32 v222, v228, v194
	ds_bpermute_b32 v223, v228, v195
	ds_bpermute_b32 v224, v228, v196
	ds_bpermute_b32 v225, v228, v197
	ds_bpermute_b32 v226, v228, v204
	ds_bpermute_b32 v227, v228, v205
	s_waitcnt lgkmcnt(7)
	v_add_f32_e32 v192, v192, v220
	s_waitcnt lgkmcnt(6)
	v_add_f32_e32 v193, v193, v221
	s_waitcnt lgkmcnt(5)
	v_add_f32_e32 v194, v194, v222
	s_waitcnt lgkmcnt(4)
	v_add_f32_e32 v195, v195, v223
	s_waitcnt lgkmcnt(3)
	v_add_f32_e32 v196, v196, v224
	s_waitcnt lgkmcnt(2)
	v_add_f32_e32 v197, v197, v225
	s_waitcnt lgkmcnt(1)
	v_add_f32_e32 v204, v204, v226
	s_waitcnt lgkmcnt(0)
	v_add_f32_e32 v205, v205, v227
	ds_bpermute_b32 v220, v229, v192
	ds_bpermute_b32 v221, v229, v193
	ds_bpermute_b32 v222, v229, v194
	ds_bpermute_b32 v223, v229, v195
	ds_bpermute_b32 v224, v229, v196
	ds_bpermute_b32 v225, v229, v197
	ds_bpermute_b32 v226, v229, v204
	ds_bpermute_b32 v227, v229, v205
	s_waitcnt lgkmcnt(7)
	v_add_f32_e32 v192, v192, v220
	s_waitcnt lgkmcnt(6)
	v_add_f32_e32 v193, v193, v221
	s_waitcnt lgkmcnt(5)
	v_add_f32_e32 v194, v194, v222
	s_waitcnt lgkmcnt(4)
	v_add_f32_e32 v195, v195, v223
	s_waitcnt lgkmcnt(3)
	v_add_f32_e32 v196, v196, v224
	s_waitcnt lgkmcnt(2)
	v_add_f32_e32 v197, v197, v225
	s_waitcnt lgkmcnt(1)
	v_add_f32_e32 v204, v204, v226
	s_waitcnt lgkmcnt(0)
	v_add_f32_e32 v205, v205, v227
	v_fmamk_f32 v192, v192, 0x3a800000, v208
	v_fmamk_f32 v193, v193, 0x3a800000, v208
	v_fmamk_f32 v194, v194, 0x3a800000, v208
	v_fmamk_f32 v195, v195, 0x3a800000, v208
	v_fmamk_f32 v196, v196, 0x3a800000, v208
	v_fmamk_f32 v197, v197, 0x3a800000, v208
	v_fmamk_f32 v204, v204, 0x3a800000, v208
	v_fmamk_f32 v205, v205, 0x3a800000, v208
	v_rsq_f32_e32 v242, v192
	v_rsq_f32_e32 v243, v193
	v_rsq_f32_e32 v244, v194
	v_rsq_f32_e32 v245, v195
	v_rsq_f32_e32 v246, v196
	v_rsq_f32_e32 v247, v197
	v_rsq_f32_e32 v248, v204
	v_rsq_f32_e32 v249, v205
.Lsc_nonext2:
	s_mov_b32 s31, 0x800000
	s_mov_b32 s99, 0x800000
	s_mov_b32 s70, 0xbfb8aa3b
	s_movk_i32 s71, 0x1c00
	s_movk_i32 s73, 0x5a
	s_mov_b64 s[40:41], -1
	s_andn2_b64 vcc, exec, s[2:3]
	s_cbranch_vccnz .LBB0_681
	s_andn2_b64 vcc, exec, s[26:27]
	s_cbranch_vccnz .LBB0_680
	s_barrier
	s_branch .LBB0_680
